# streaming (nt) stores for Qeff/M/Bc outputs of the hand-written unit final stages
# baseline (speedup 1.0000x reference)
; __device__ __forceinline__ bf16_t f2bf(float f) { return (bf16_t)(pk2(f, 0.f) & 0xffffu); }
; __device__ __forceinline__ float fexp(float x) { return __expf(x); }
; #define LBAR() do { asm volatile("s_waitcnt lgkmcnt(0)" ::: "memory"); __builtin_amdgcn_s_barrier(); asm volatile("" ::: "memory"); } while (0)
; __device__ __forceinline__ void hgrn_unit(const Ctx& X, LAS unsigned char* hl, int b, int c, int h, int tid_h, int w4, int lane, int layer) {
;     ...
; #pragma unroll
;         for (int ct = 0; ct < 4; ++ct)
; #pragma unroll
;             for (int j = 0; j < 4; ++j) { const int ii = 16 * I + 4 * q + j, col = 16 * ct + r;
;                 QT[ii * LT + col] = f2bf((ct <= I && ii >= col) ? acc[ct][j] : 0.f); }
;     }
;     LBAR();
;     {
; #pragma unroll
;         for (int e = 0; e < 16; ++e) { VT[(ds + e) * LT + i] = f2bf(vv[e]); KDT[(ds + e) * LT + i] = f2bf(kk[e] * fexp(G63[e] - Gi[e])); }
;     }
.LBB0_317:
	v_ashrrev_i32_e32 v96, 4, v130
	v_lshl_add_u32 v98, v96, 2, s39
	v_cmp_ge_i32_e32 vcc, v98, v91
	v_lshlrev_b32_e32 v99, 1, v91
	v_mul_lo_u32 v100, v98, s44
	v_cndmask_b32_e32 v18, 0, v18, vcc
	s_waitcnt lgkmcnt(0)
	v_cvt_pk_bf16_f32 v18, v18, v157
	v_add3_u32 v74, v74, v99, v100
	ds_write_b16 v74, v18
	v_or_b32_e32 v18, 1, v98
	v_cmp_ge_i32_e32 vcc, v18, v91
	v_or_b32_e32 v99, 16, v91
	v_readlane_b32 s6, v252, 48
	v_cndmask_b32_e32 v19, 0, v19, vcc
	v_cvt_pk_bf16_f32 v19, v19, v157
	ds_write_b16 v74, v19 offset:144
	v_or_b32_e32 v19, 2, v98
	v_cmp_ge_i32_e32 vcc, v19, v91
	v_readlane_b32 s7, v252, 49
	v_or_b32_e32 v22, 48, v91
	v_cndmask_b32_e32 v20, 0, v20, vcc
	v_cvt_pk_bf16_f32 v20, v20, v157
	ds_write_b16 v74, v20 offset:288
	v_or_b32_e32 v20, 3, v98
	v_cmp_ge_i32_e32 vcc, v20, v91
	v_and_b32_e32 v97, 0xffff0000, v6
	v_lshlrev_b32_e32 v6, 16, v6
	v_cndmask_b32_e32 v21, 0, v21, vcc
	v_cmp_lt_i32_e32 vcc, v98, v99
	s_or_b64 s[4:5], s[40:41], vcc
	v_cndmask_b32_e64 v14, v14, 0, s[4:5]
	v_cmp_lt_i32_e32 vcc, v18, v99
	v_cvt_pk_bf16_f32 v21, v21, v157
	ds_write_b16 v74, v21 offset:432
	v_cvt_pk_bf16_f32 v14, v14, v157
	s_or_b64 s[4:5], s[40:41], vcc
	ds_write_b16 v74, v14 offset:32
	v_cndmask_b32_e64 v14, v15, 0, s[4:5]
	v_cmp_lt_i32_e32 vcc, v19, v99
	v_cvt_pk_bf16_f32 v14, v14, v157
	s_or_b64 s[4:5], s[40:41], vcc
	ds_write_b16 v74, v14 offset:176
	v_cndmask_b32_e64 v14, v16, 0, s[4:5]
	v_cmp_lt_i32_e32 vcc, v20, v99
	v_cvt_pk_bf16_f32 v14, v14, v157
	s_or_b64 s[4:5], s[40:41], vcc
	ds_write_b16 v74, v14 offset:320
	v_cndmask_b32_e64 v14, v17, 0, s[4:5]
	v_cvt_pk_bf16_f32 v14, v14, v157
	ds_write_b16 v74, v14 offset:464
	v_or_b32_e32 v14, 32, v91
	v_cmp_lt_i32_e32 vcc, v98, v14
	s_or_b64 s[4:5], s[6:7], vcc
	v_cndmask_b32_e64 v15, v30, 0, s[4:5]
	v_cmp_lt_i32_e32 vcc, v18, v14
	v_cvt_pk_bf16_f32 v15, v15, v157
	s_or_b64 s[4:5], s[6:7], vcc
	ds_write_b16 v74, v15 offset:64
	v_cndmask_b32_e64 v15, v31, 0, s[4:5]
	v_cmp_lt_i32_e32 vcc, v19, v14
	v_cvt_pk_bf16_f32 v15, v15, v157
	s_or_b64 s[4:5], s[6:7], vcc
	v_cmp_lt_i32_e32 vcc, v20, v14
	ds_write_b16 v74, v15 offset:208
	v_cndmask_b32_e64 v15, v32, 0, s[4:5]
	s_or_b64 s[4:5], s[6:7], vcc
	v_readlane_b32 s6, v252, 52
	v_cndmask_b32_e64 v14, v33, 0, s[4:5]
	v_cmp_lt_i32_e32 vcc, v98, v22
	v_readlane_b32 s7, v252, 53
	v_cvt_pk_bf16_f32 v15, v15, v157
	ds_write_b16 v74, v15 offset:352
	v_cvt_pk_bf16_f32 v14, v14, v157
	s_or_b64 s[4:5], s[6:7], vcc
	ds_write_b16 v74, v14 offset:496
	v_cndmask_b32_e64 v14, v34, 0, s[4:5]
	v_cmp_lt_i32_e32 vcc, v18, v22
	v_cvt_pk_bf16_f32 v14, v14, v157
	s_or_b64 s[4:5], s[6:7], vcc
	ds_write_b16 v74, v14 offset:96
	v_cndmask_b32_e64 v14, v35, 0, s[4:5]
	v_cmp_lt_i32_e32 vcc, v19, v22
	v_cvt_pk_bf16_f32 v14, v14, v157
	s_or_b64 s[4:5], s[6:7], vcc
	ds_write_b16 v74, v14 offset:240
	v_cndmask_b32_e64 v14, v36, 0, s[4:5]
	v_cmp_lt_i32_e32 vcc, v20, v22
	v_cvt_pk_bf16_f32 v14, v14, v157
	s_or_b64 s[4:5], s[6:7], vcc
	v_sub_f32_e32 v15, v40, v38
	ds_write_b16 v74, v14 offset:384
	v_cndmask_b32_e64 v14, v37, 0, s[4:5]
	v_mul_f32_e32 v15, 0x3fb8aa3b, v15
	v_cvt_pk_bf16_f32 v14, v14, v157
	v_exp_f32_e32 v15, v15
	ds_write_b16 v74, v14 offset:528
	v_mul_u32_u24_e32 v14, 0x48, v73
	v_add_lshl_u32 v14, v14, v72, 1
	s_waitcnt lgkmcnt(0)
	s_barrier
	v_cvt_pk_bf16_f32 v6, v6, v157
	v_add_u32_e32 v16, v71, v14
	ds_write_b16 v16, v6
	v_mul_f32_e32 v6, v90, v15
	v_sub_f32_e32 v15, v41, v39
	v_mul_f32_e32 v15, 0x3fb8aa3b, v15
	v_exp_f32_e32 v15, v15
	v_cvt_pk_bf16_f32 v6, v6, v157
	v_add_u32_e32 v14, v70, v14
	ds_write_b16 v14, v6
	v_cvt_pk_bf16_f32 v6, v97, v157
	ds_write_b16 v16, v6 offset:144
	v_mul_f32_e32 v6, v89, v15
	v_sub_f32_e32 v15, v44, v42
	v_mul_f32_e32 v15, 0x3fb8aa3b, v15
	v_and_b32_e32 v29, 0xffff0000, v7
	v_lshlrev_b32_e32 v7, 16, v7
	v_cvt_pk_bf16_f32 v6, v6, v157
	v_exp_f32_e32 v15, v15
	ds_write_b16 v14, v6 offset:144
	v_cvt_pk_bf16_f32 v6, v7, v157
	v_sub_f32_e32 v7, v45, v43
	v_mul_f32_e32 v7, 0x3fb8aa3b, v7
	v_exp_f32_e32 v7, v7
	ds_write_b16 v16, v6 offset:288
	v_mul_f32_e32 v6, v88, v15
	v_cvt_pk_bf16_f32 v6, v6, v157
	ds_write_b16 v14, v6 offset:288
	v_cvt_pk_bf16_f32 v6, v29, v157
	ds_write_b16 v16, v6 offset:432
	v_mul_f32_e32 v6, v87, v7
	v_sub_f32_e32 v7, v48, v46
	v_mul_f32_e32 v7, 0x3fb8aa3b, v7
	v_exp_f32_e32 v7, v7
	v_cvt_pk_bf16_f32 v6, v6, v157
	v_and_b32_e32 v28, 0xffff0000, v8
	v_lshlrev_b32_e32 v8, 16, v8
	ds_write_b16 v14, v6 offset:432
	v_cvt_pk_bf16_f32 v6, v8, v157
	ds_write_b16 v16, v6 offset:576
	v_mul_f32_e32 v6, v86, v7
	v_sub_f32_e32 v7, v49, v47
	v_mul_f32_e32 v7, 0x3fb8aa3b, v7
	v_exp_f32_e32 v7, v7
	v_cvt_pk_bf16_f32 v6, v6, v157
	ds_write_b16 v14, v6 offset:576
	v_cvt_pk_bf16_f32 v6, v28, v157
	ds_write_b16 v16, v6 offset:720
	v_mul_f32_e32 v6, v85, v7
	v_sub_f32_e32 v7, v52, v50
	v_mul_f32_e32 v7, 0x3fb8aa3b, v7
	v_exp_f32_e32 v7, v7
	v_cvt_pk_bf16_f32 v6, v6, v157
	v_and_b32_e32 v27, 0xffff0000, v9
	v_lshlrev_b32_e32 v9, 16, v9
	ds_write_b16 v14, v6 offset:720
	v_cvt_pk_bf16_f32 v6, v9, v157
	ds_write_b16 v16, v6 offset:864
	v_mul_f32_e32 v6, v84, v7
	v_sub_f32_e32 v7, v53, v51
	v_mul_f32_e32 v7, 0x3fb8aa3b, v7
	v_exp_f32_e32 v7, v7
	v_cvt_pk_bf16_f32 v6, v6, v157
	ds_write_b16 v14, v6 offset:864
	v_cvt_pk_bf16_f32 v6, v27, v157
	ds_write_b16 v16, v6 offset:1008
	v_mul_f32_e32 v6, v83, v7
	v_sub_f32_e32 v7, v56, v54
	v_mul_f32_e32 v7, 0x3fb8aa3b, v7
	v_exp_f32_e32 v7, v7
	v_cvt_pk_bf16_f32 v6, v6, v157
	s_waitcnt vmcnt(2)
; __device__ __forceinline__ bf16_t f2bf(float f) { return (bf16_t)(pk2(f, 0.f) & 0xffffu); }
; __device__ __forceinline__ float fexp(float x) { return __expf(x); }
; #define LBAR() do { asm volatile("s_waitcnt lgkmcnt(0)" ::: "memory"); __builtin_amdgcn_s_barrier(); asm volatile("" ::: "memory"); } while (0)
; __device__ __forceinline__ void hgrn_unit(const Ctx& X, LAS unsigned char* hl, int b, int c, int h, int tid_h, int w4, int lane, int layer) {
;     ...
;         for (int e = 0; e < 16; ++e) { VT[(ds + e) * LT + i] = f2bf(vv[e]); KDT[(ds + e) * LT + i] = f2bf(kk[e] * fexp(G63[e] - Gi[e])); }
;     }
;     LBAR();
; #pragma unroll
;     for (int ct = 0; ct < 4; ++ct) acc[ct] = mma16(QT, 16 * w4, VT, 16 * ct, (f32x4){0.f, 0.f, 0.f, 0.f}, r, q);
;     store_oloc(WSP(bf16_t, WS_OLOC), uid, w4, lane, acc);
; #pragma unroll
;     for (int ct = 0; ct < 4; ++ct) acc[ct] = mma16(KDT, 16 * w4, VT, 16 * ct, (f32x4){0.f, 0.f, 0.f, 0.f}, r, q);
;     store_bc(WSP(bf16_t, WS_BCS), uid, w4, r, q, acc);
;     LBAR();
	v_and_b32_e32 v26, 0xffff0000, v10
	v_lshlrev_b32_e32 v10, 16, v10
	ds_write_b16 v14, v6 offset:1008
	v_cvt_pk_bf16_f32 v6, v10, v157
	ds_write_b16 v16, v6 offset:1152
	v_mul_f32_e32 v6, v82, v7
	v_sub_f32_e32 v7, v57, v55
	v_mul_f32_e32 v7, 0x3fb8aa3b, v7
	v_exp_f32_e32 v7, v7
	v_cvt_pk_bf16_f32 v6, v6, v157
	ds_write_b16 v14, v6 offset:1152
	v_cvt_pk_bf16_f32 v6, v26, v157
	ds_write_b16 v16, v6 offset:1296
	v_mul_f32_e32 v6, v81, v7
	v_sub_f32_e32 v7, v60, v58
	v_mul_f32_e32 v7, 0x3fb8aa3b, v7
	v_exp_f32_e32 v7, v7
	v_cvt_pk_bf16_f32 v6, v6, v157
	v_and_b32_e32 v25, 0xffff0000, v11
	v_lshlrev_b32_e32 v11, 16, v11
	ds_write_b16 v14, v6 offset:1296
	v_cvt_pk_bf16_f32 v6, v11, v157
	ds_write_b16 v16, v6 offset:1440
	v_mul_f32_e32 v6, v80, v7
	v_sub_f32_e32 v7, v61, v59
	v_mul_f32_e32 v7, 0x3fb8aa3b, v7
	v_exp_f32_e32 v7, v7
	v_cvt_pk_bf16_f32 v6, v6, v157
	ds_write_b16 v14, v6 offset:1440
	v_cvt_pk_bf16_f32 v6, v25, v157
	ds_write_b16 v16, v6 offset:1584
	v_mul_f32_e32 v6, v79, v7
	v_sub_f32_e32 v7, v64, v62
	v_mul_f32_e32 v7, 0x3fb8aa3b, v7
	v_exp_f32_e32 v7, v7
	v_cvt_pk_bf16_f32 v6, v6, v157
	v_and_b32_e32 v24, 0xffff0000, v12
	v_lshlrev_b32_e32 v12, 16, v12
	ds_write_b16 v14, v6 offset:1584
	v_cvt_pk_bf16_f32 v6, v12, v157
	ds_write_b16 v16, v6 offset:1728
	v_mul_f32_e32 v6, v78, v7
	v_sub_f32_e32 v7, v65, v63
	v_mul_f32_e32 v7, 0x3fb8aa3b, v7
	v_exp_f32_e32 v7, v7
	v_cvt_pk_bf16_f32 v6, v6, v157
	ds_write_b16 v14, v6 offset:1728
	v_cvt_pk_bf16_f32 v6, v24, v157
	ds_write_b16 v16, v6 offset:1872
	v_mul_f32_e32 v6, v77, v7
	v_sub_f32_e32 v7, v68, v66
	v_mul_f32_e32 v7, 0x3fb8aa3b, v7
	v_exp_f32_e32 v7, v7
	v_cvt_pk_bf16_f32 v6, v6, v157
	v_and_b32_e32 v23, 0xffff0000, v13
	v_lshlrev_b32_e32 v13, 16, v13
	ds_write_b16 v14, v6 offset:1872
	v_cvt_pk_bf16_f32 v6, v13, v157
	ds_write_b16 v16, v6 offset:2016
	v_mul_f32_e32 v6, v76, v7
	v_sub_f32_e32 v7, v69, v67
	v_mul_f32_e32 v7, 0x3fb8aa3b, v7
	v_exp_f32_e32 v7, v7
	v_cvt_pk_bf16_f32 v6, v6, v157
	ds_write_b16 v14, v6 offset:2016
	v_cvt_pk_bf16_f32 v6, v23, v157
	ds_write_b16 v16, v6 offset:2160
	v_mul_f32_e32 v6, v75, v7
	v_cvt_pk_bf16_f32 v6, v6, v157
	ds_write_b16 v14, v6 offset:2160
	s_waitcnt lgkmcnt(0)
	s_barrier
	v_add_u32_e32 v22, v71, v92
	v_add_u32_e32 v44, v22, v95
	v_mad_u32_u24 v34, v99, s44, v22
	v_mul_u32_u24_e32 v26, 0x90, v93
	v_add3_u32 v18, v70, v26, v92
	ds_read_b128 v[46:49], v94
	ds_read_b128 v[50:53], v94 offset:64
	ds_read_b128 v[54:57], v44
	ds_read_b128 v[58:61], v44 offset:64
	ds_read_b128 v[62:65], v34
	ds_read_b128 v[66:69], v34 offset:64
	ds_read_b128 v[72:75], v34 offset:2304
	ds_read_b128 v[76:79], v34 offset:2368
	ds_read_b128 v[80:83], v44 offset:6912
	ds_read_b128 v[102:105], v44 offset:6976
	ds_read_b128 v[134:137], v18
	ds_read_b128 v[138:141], v18 offset:64
	s_add_u32 s4, s79, s0
	s_addc_u32 s5, s80, s1
	s_add_u32 s0, s74, s0
	s_addc_u32 s1, s75, s1
	v_lshlrev_b32_e32 v42, 4, v130
	v_ashrrev_i32_e32 v43, 31, v42
	v_lshl_add_u64 v[38:39], v[42:43], 1, s[4:5]
	v_lshl_or_b32 v12, v91, 2, s81
	v_lshl_add_u32 v12, v96, 6, v12
	v_ashrrev_i32_e32 v13, 31, v12
	v_lshl_add_u64 v[14:15], v[12:13], 1, s[0:1]
	v_add_u32_e32 v16, 0x800, v12
	v_ashrrev_i32_e32 v17, 31, v16
	v_lshl_add_u64 v[16:17], v[16:17], 1, s[0:1]
	v_add_u32_e32 v20, 0xc00, v12
	v_ashrrev_i32_e32 v21, 31, v20
	v_lshl_add_u64 v[20:21], v[20:21], 1, s[0:1]
	s_waitcnt lgkmcnt(2)
	v_mfma_f32_16x16x32_bf16 v[186:189], v[46:49], v[54:57], 0
	v_mfma_f32_16x16x32_bf16 v[190:193], v[46:49], v[62:65], 0
	v_mfma_f32_16x16x32_bf16 v[194:197], v[46:49], v[72:75], 0
	v_mfma_f32_16x16x32_bf16 v[198:201], v[46:49], v[80:83], 0
	v_mfma_f32_16x16x32_bf16 v[186:189], v[50:53], v[58:61], v[186:189]
	v_mfma_f32_16x16x32_bf16 v[190:193], v[50:53], v[66:69], v[190:193]
	v_mfma_f32_16x16x32_bf16 v[194:197], v[50:53], v[76:79], v[194:197]
	v_mfma_f32_16x16x32_bf16 v[198:201], v[50:53], v[102:105], v[198:201]
	s_waitcnt lgkmcnt(0)
	v_mfma_f32_16x16x32_bf16 v[202:205], v[134:137], v[54:57], 0
	v_mfma_f32_16x16x32_bf16 v[206:209], v[134:137], v[62:65], 0
	v_mfma_f32_16x16x32_bf16 v[210:213], v[134:137], v[72:75], 0
	v_mfma_f32_16x16x32_bf16 v[214:217], v[134:137], v[80:83], 0
	v_mfma_f32_16x16x32_bf16 v[202:205], v[138:141], v[58:61], v[202:205]
	v_mfma_f32_16x16x32_bf16 v[206:209], v[138:141], v[66:69], v[206:209]
	v_mfma_f32_16x16x32_bf16 v[210:213], v[138:141], v[76:79], v[210:213]
	v_mfma_f32_16x16x32_bf16 v[214:217], v[138:141], v[102:105], v[214:217]
	v_cvt_pk_bf16_f32 v218, v186, v187
	v_cvt_pk_bf16_f32 v219, v188, v189
	v_cvt_pk_bf16_f32 v220, v190, v191
	v_cvt_pk_bf16_f32 v221, v192, v193
	v_cvt_pk_bf16_f32 v236, v194, v195
	v_cvt_pk_bf16_f32 v237, v196, v197
	v_cvt_pk_bf16_f32 v238, v198, v199
	v_cvt_pk_bf16_f32 v239, v200, v201
	global_store_dwordx4 v[38:39], v[218:221], off nt
	global_store_dwordx4 v[38:39], v[236:239], off offset:16 nt
	v_cvt_pk_bf16_f32 v246, v202, v203
	v_cvt_pk_bf16_f32 v247, v204, v205
	v_cvt_pk_bf16_f32 v248, v206, v207
	v_cvt_pk_bf16_f32 v249, v208, v209
	v_cvt_pk_bf16_f32 v250, v210, v211
	v_cvt_pk_bf16_f32 v251, v212, v213
	v_cvt_pk_bf16_f32 v226, v214, v215
	v_cvt_pk_bf16_f32 v227, v216, v217
	global_store_dwordx2 v[14:15], v[246:247], off nt
	global_store_dwordx2 v[14:15], v[248:249], off offset:2048 nt
	global_store_dwordx2 v[16:17], v[250:251], off nt
	global_store_dwordx2 v[20:21], v[226:227], off nt
	s_waitcnt lgkmcnt(0)
	s_barrier
	s_mov_b64 s[0:1], 0

; __device__ __forceinline__ float bf2f(bf16_t b) { return __uint_as_float((unsigned)b << 16); }
; __device__ __forceinline__ bf16_t f2bf(float f) { return (bf16_t)(pk2(f, 0.f) & 0xffffu); }
; __device__ __forceinline__ float fexp(float x) { return __expf(x); }
; __device__ __forceinline__ void gdn_unit(const Ctx& X, LAS unsigned char* hl, int b, int c, int h, int tid_h, int w4, int lane, int layer) {
;     ...
;     {
;         f32x4 acc[4];
;         const float eG63 = fexp(Gs[63]);
; #pragma unroll
;         for (int ct = 0; ct < 4; ++ct) acc[ct] = mma16(P, 16 * w4, WT, 16 * ct, (f32x4){0.f, 0.f, 0.f, 0.f}, r, q);
;         bf16_t* qe = WSP(bf16_t, WS_QEFF) + (size_t)uid * 4096;
; #pragma unroll
;         for (int ct = 0; ct < 4; ++ct)
; #pragma unroll
;             for (int j = 0; j < 4; ++j) { const int ii = 16 * w4 + 4 * q + j, col = 16 * ct + r;
;                 qe[ii * 64 + col] = f2bf(bf2f(Q[ii * LT + col]) * fexp(Gs[ii]) - acc[ct][j]); }
; #pragma unroll
;         for (int ct = 0; ct < 4; ++ct) acc[ct] = mma16(P, 16 * w4, UT, 16 * ct, (f32x4){0.f, 0.f, 0.f, 0.f}, r, q);
;         store_oloc(WSP(bf16_t, WS_OLOC), uid, w4, lane, acc);
; #pragma unroll
;         for (int ct = 0; ct < 4; ++ct) acc[ct] = mma16(KDT, 16 * w4, WT, 16 * ct, (f32x4){0.f, 0.f, 0.f, 0.f}, r, q);
;         bf16_t* mm = WSP(bf16_t, WS_MM) + (size_t)(uid - 2048) * 4096;
; #pragma unroll
;         for (int ct = 0; ct < 4; ++ct)
; #pragma unroll
;             for (int j = 0; j < 4; ++j) { const int ii = 16 * w4 + 4 * q + j, col = 16 * ct + r;
;                 mm[((w4 * 2 + (ct >> 1)) * 64 + (r >> 2) * 16 + 4 * q + j) * 8 + (ct & 1) * 4 + (r & 3)] = f2bf((ii == col ? eG63 : 0.f) - acc[ct][j]); }
; #pragma unroll
;         for (int ct = 0; ct < 4; ++ct) acc[ct] = mma16(KDT, 16 * w4, UT, 16 * ct, (f32x4){0.f, 0.f, 0.f, 0.f}, r, q);
;         store_bc(WSP(bf16_t, WS_BCS), uid, w4, r, q, acc);
;     }
.LBB0_619:
	s_waitcnt lgkmcnt(0)
	s_barrier
	v_bfe_u32 v54, v224, 6, 2
	v_and_b32_e32 v55, 15, v232
	v_lshrrev_b32_e32 v56, 4, v232
	v_lshl_or_b32 v57, v54, 4, v55
	v_mul_u32_u24_e32 v58, 0x90, v57
	v_mul_u32_u24_e32 v59, 0x90, v55
	v_lshl_add_u32 v60, v56, 4, v58
	v_lshl_add_u32 v61, v56, 4, v59
	v_add_u32_e32 v60, v182, v60
	v_add_u32_e32 v61, v182, v61
	v_add_u32_e32 v178, 0xb400, v60
	v_add_u32_e32 v179, 0x4800, v61
	v_add_u32_e32 v60, 0x9000, v60
	v_add_u32_e32 v61, 0x6c00, v61
	ds_read_b128 v[6:9], v178
	ds_read_b128 v[10:13], v178 offset:64
	ds_read_b128 v[22:25], v179
	ds_read_b128 v[26:29], v179 offset:64
	ds_read_b128 v[30:33], v179 offset:2304
	ds_read_b128 v[34:37], v179 offset:2368
	ds_read_b128 v[38:41], v179 offset:4608
	ds_read_b128 v[42:45], v179 offset:4672
	ds_read_b128 v[46:49], v179 offset:6912
	ds_read_b128 v[50:53], v179 offset:6976
	ds_read_b128 v[14:17], v60
	ds_read_b128 v[18:21], v60 offset:64
	v_lshl_add_u32 v62, v57, 2, v185
	v_lshl_add_u32 v63, v56, 3, v58
	v_add_u32_e32 v63, v182, v63
	ds_read_b32 v176, v62
	ds_read_b32 v177, v185 offset:252
	s_lshl_b32 s0, s22, 9
	s_lshl_b32 s1, s23, 7
	s_add_i32 s1, s1, s0
	s_or_b32 s0, s1, s21
	s_ashr_i32 s1, s0, 31
	s_lshl_b64 s[0:1], s[0:1], 13
	s_add_u32 s4, s89, s0
	s_addc_u32 s5, s78, s1
	s_add_u32 s6, s79, s0
	s_addc_u32 s7, s80, s1
	v_readlane_b32 s98, v253, 3
	v_readlane_b32 s99, v253, 4
	s_add_u32 s98, s98, s0
	s_addc_u32 s99, s99, s1
	s_add_u32 s98, s98, 0xff000000
	s_addc_u32 s99, s99, -1
	s_add_u32 s100, s74, s0
	s_addc_u32 s101, s75, s1
	v_readfirstlane_b32 s32, v54
	v_lshlrev_b32_e32 v64, 11, v54
	v_lshlrev_b32_e32 v65, 5, v232
	v_lshl_add_u32 v64, v232, 4, v64
	v_lshlrev_b32_e32 v66, 9, v54
	v_lshl_add_u32 v66, v232, 3, v66
	v_add_u32_e32 v67, 0x1000, v66
	v_lshlrev_b32_e32 v71, 7, v57
	v_lshl_add_u32 v71, v56, 3, v71
	v_lshlrev_b32_e32 v70, 2, v56
	v_sub_u32_e32 v70, v55, v70
	s_waitcnt lgkmcnt(4)
	v_mfma_f32_16x16x32_bf16 v[134:137], v[22:25], v[6:9], 0
	v_mfma_f32_16x16x32_bf16 v[138:141], v[30:33], v[6:9], 0
	v_mfma_f32_16x16x32_bf16 v[142:145], v[38:41], v[6:9], 0
	v_mfma_f32_16x16x32_bf16 v[146:149], v[46:49], v[6:9], 0
	v_mfma_f32_16x16x32_bf16 v[134:137], v[26:29], v[10:13], v[134:137]
	v_mfma_f32_16x16x32_bf16 v[138:141], v[34:37], v[10:13], v[138:141]
	v_mfma_f32_16x16x32_bf16 v[142:145], v[42:45], v[10:13], v[142:145]
	v_mfma_f32_16x16x32_bf16 v[146:149], v[50:53], v[10:13], v[146:149]
	ds_read_b64 v[150:151], v63
	ds_read_b64 v[152:153], v63 offset:32
	ds_read_b64 v[172:173], v63 offset:64
	ds_read_b64 v[174:175], v63 offset:96
	ds_read_b128 v[186:189], v61
	ds_read_b128 v[190:193], v61 offset:64
	ds_read_b128 v[194:197], v61 offset:2304
	ds_read_b128 v[198:201], v61 offset:2368
	ds_read_b128 v[202:205], v61 offset:4608
	ds_read_b128 v[206:209], v61 offset:4672
	ds_read_b128 v[210:213], v61 offset:6912
	s_waitcnt lgkmcnt(13)
	v_mfma_f32_16x16x32_bf16 v[236:239], v[22:25], v[14:17], 0
	v_mfma_f32_16x16x32_bf16 v[240:243], v[30:33], v[14:17], 0
	v_mfma_f32_16x16x32_bf16 v[244:247], v[38:41], v[14:17], 0
	v_mfma_f32_16x16x32_bf16 v[248:251], v[46:49], v[14:17], 0
	v_mfma_f32_16x16x32_bf16 v[236:239], v[26:29], v[18:21], v[236:239]
	v_mfma_f32_16x16x32_bf16 v[240:243], v[34:37], v[18:21], v[240:243]
	v_mfma_f32_16x16x32_bf16 v[244:247], v[42:45], v[18:21], v[244:247]
	v_mfma_f32_16x16x32_bf16 v[248:251], v[50:53], v[18:21], v[248:251]
	ds_read_b128 v[214:217], v61 offset:6976
	s_waitcnt lgkmcnt(8)
	v_mul_f32_e32 v176, 0x3fb8aa3b, v176
	v_mul_f32_e32 v177, 0x3fb8aa3b, v177
	v_exp_f32_e32 v176, v176
	v_exp_f32_e32 v177, v177
	v_cmp_eq_u32_e32 vcc, 0, v70
	v_cmp_eq_u32_e64 s[0:1], 1, v70
	v_lshlrev_b32_e32 v76, 16, v150
	v_and_b32_e32 v77, 0xffff0000, v150
	v_cndmask_b32_e32 v72, 0, v177, vcc
	v_cndmask_b32_e64 v73, 0, v177, s[0:1]
	v_cmp_eq_u32_e32 vcc, 2, v70
	v_cmp_eq_u32_e64 s[0:1], 3, v70
	v_lshlrev_b32_e32 v78, 16, v151
	v_and_b32_e32 v79, 0xffff0000, v151
	v_cndmask_b32_e32 v74, 0, v177, vcc
	v_cndmask_b32_e64 v75, 0, v177, s[0:1]
	s_waitcnt lgkmcnt(0)
	v_mfma_f32_16x16x32_bf16 v[84:87], v[6:9], v[186:189], 0
	v_mfma_f32_16x16x32_bf16 v[88:91], v[6:9], v[194:197], 0
	v_mfma_f32_16x16x32_bf16 v[92:95], v[6:9], v[202:205], 0
	v_mfma_f32_16x16x32_bf16 v[96:99], v[6:9], v[210:213], 0
	v_mfma_f32_16x16x32_bf16 v[114:117], v[14:17], v[186:189], 0
	v_mfma_f32_16x16x32_bf16 v[118:121], v[14:17], v[194:197], 0
	v_mfma_f32_16x16x32_bf16 v[122:125], v[14:17], v[202:205], 0
	v_mfma_f32_16x16x32_bf16 v[126:129], v[14:17], v[210:213], 0
	v_mfma_f32_16x16x32_bf16 v[84:87], v[10:13], v[190:193], v[84:87]
	v_mfma_f32_16x16x32_bf16 v[88:91], v[10:13], v[198:201], v[88:91]
	v_mfma_f32_16x16x32_bf16 v[92:95], v[10:13], v[206:209], v[92:95]
	v_mfma_f32_16x16x32_bf16 v[96:99], v[10:13], v[214:217], v[96:99]
	v_mfma_f32_16x16x32_bf16 v[114:117], v[18:21], v[190:193], v[114:117]
	v_mfma_f32_16x16x32_bf16 v[118:121], v[18:21], v[198:201], v[118:121]
	v_mfma_f32_16x16x32_bf16 v[122:125], v[18:21], v[206:209], v[122:125]
	v_mfma_f32_16x16x32_bf16 v[126:129], v[18:21], v[214:217], v[126:129]
	v_fma_f32 v76, v176, v76, -v134
	v_fma_f32 v77, v176, v77, -v135
	v_fma_f32 v78, v176, v78, -v136
	v_fma_f32 v79, v176, v79, -v137
	v_cvt_pk_bf16_f32 v218, v76, v77
	v_cvt_pk_bf16_f32 v219, v78, v79
	global_store_dwordx2 v71, v[218:219], s[4:5] nt
	v_lshlrev_b32_e32 v76, 16, v152
	v_and_b32_e32 v77, 0xffff0000, v152
	v_lshlrev_b32_e32 v78, 16, v153
	v_and_b32_e32 v79, 0xffff0000, v153
	v_fma_f32 v76, v176, v76, -v138
	v_fma_f32 v77, v176, v77, -v139
	v_fma_f32 v78, v176, v78, -v140
	v_fma_f32 v79, v176, v79, -v141
	v_cvt_pk_bf16_f32 v220, v76, v77
	v_cvt_pk_bf16_f32 v221, v78, v79
; __device__ __forceinline__ bf16_t f2bf(float f) { return (bf16_t)(pk2(f, 0.f) & 0xffffu); }
; #define LBAR() do { asm volatile("s_waitcnt lgkmcnt(0)" ::: "memory"); __builtin_amdgcn_s_barrier(); asm volatile("" ::: "memory"); } while (0)
; __device__ __forceinline__ void gdn_unit(const Ctx& X, LAS unsigned char* hl, int b, int c, int h, int tid_h, int w4, int lane, int layer) {
;     ...
;         bf16_t* mm = WSP(bf16_t, WS_MM) + (size_t)(uid - 2048) * 4096;
; #pragma unroll
;         for (int ct = 0; ct < 4; ++ct)
; #pragma unroll
;             for (int j = 0; j < 4; ++j) { const int ii = 16 * w4 + 4 * q + j, col = 16 * ct + r;
;                 mm[((w4 * 2 + (ct >> 1)) * 64 + (r >> 2) * 16 + 4 * q + j) * 8 + (ct & 1) * 4 + (r & 3)] = f2bf((ii == col ? eG63 : 0.f) - acc[ct][j]); }
; #pragma unroll
;         for (int ct = 0; ct < 4; ++ct) acc[ct] = mma16(KDT, 16 * w4, UT, 16 * ct, (f32x4){0.f, 0.f, 0.f, 0.f}, r, q);
;         store_bc(WSP(bf16_t, WS_BCS), uid, w4, r, q, acc);
;     }
;     LBAR();
	global_store_dwordx2 v71, v[220:221], s[4:5] offset:32 nt
	v_lshlrev_b32_e32 v76, 16, v172
	v_and_b32_e32 v77, 0xffff0000, v172
	v_lshlrev_b32_e32 v78, 16, v173
	v_and_b32_e32 v79, 0xffff0000, v173
	v_fma_f32 v76, v176, v76, -v142
	v_fma_f32 v77, v176, v77, -v143
	v_fma_f32 v78, v176, v78, -v144
	v_fma_f32 v79, v176, v79, -v145
	v_cvt_pk_bf16_f32 v222, v76, v77
	v_cvt_pk_bf16_f32 v223, v78, v79
	global_store_dwordx2 v71, v[222:223], s[4:5] offset:64 nt
	v_lshlrev_b32_e32 v76, 16, v174
	v_and_b32_e32 v77, 0xffff0000, v174
	v_lshlrev_b32_e32 v78, 16, v175
	v_and_b32_e32 v79, 0xffff0000, v175
	v_fma_f32 v76, v176, v76, -v146
	v_fma_f32 v77, v176, v77, -v147
	v_fma_f32 v78, v176, v78, -v148
	v_fma_f32 v79, v176, v79, -v149
	v_cvt_pk_bf16_f32 v226, v76, v77
	v_cvt_pk_bf16_f32 v227, v78, v79
	global_store_dwordx2 v71, v[226:227], s[4:5] offset:96 nt
	s_cmp_eq_u32 s32, 0
	s_cselect_b32 s0, 1.0, 0
	v_fma_f32 v76, v72, s0, -v236
	v_fma_f32 v77, v73, s0, -v237
	v_fma_f32 v78, v74, s0, -v238
	v_fma_f32 v79, v75, s0, -v239
	v_cvt_pk_bf16_f32 v100, v76, v77
	v_cvt_pk_bf16_f32 v101, v78, v79
	s_cmp_eq_u32 s32, 1
	s_cselect_b32 s0, 1.0, 0
	v_fma_f32 v76, v72, s0, -v240
	v_fma_f32 v77, v73, s0, -v241
	v_fma_f32 v78, v74, s0, -v242
	v_fma_f32 v79, v75, s0, -v243
	v_cvt_pk_bf16_f32 v102, v76, v77
	v_cvt_pk_bf16_f32 v103, v78, v79
	global_store_dwordx4 v64, v[100:103], s[98:99] nt
	s_cmp_eq_u32 s32, 2
	s_cselect_b32 s0, 1.0, 0
	v_fma_f32 v76, v72, s0, -v244
	v_fma_f32 v77, v73, s0, -v245
	v_fma_f32 v78, v74, s0, -v246
	v_fma_f32 v79, v75, s0, -v247
	v_cvt_pk_bf16_f32 v104, v76, v77
	v_cvt_pk_bf16_f32 v105, v78, v79
	s_cmp_eq_u32 s32, 3
	s_cselect_b32 s0, 1.0, 0
	v_fma_f32 v76, v72, s0, -v248
	v_fma_f32 v77, v73, s0, -v249
	v_fma_f32 v78, v74, s0, -v250
	v_fma_f32 v79, v75, s0, -v251
	v_cvt_pk_bf16_f32 v106, v76, v77
	v_cvt_pk_bf16_f32 v107, v78, v79
	global_store_dwordx4 v64, v[104:107], s[98:99] offset:1024 nt
	v_cvt_pk_bf16_f32 v108, v84, v85
	v_cvt_pk_bf16_f32 v109, v86, v87
	v_cvt_pk_bf16_f32 v110, v88, v89
	v_cvt_pk_bf16_f32 v111, v90, v91
	global_store_dwordx4 v65, v[108:111], s[6:7] nt
	v_cvt_pk_bf16_f32 v80, v92, v93
	v_cvt_pk_bf16_f32 v81, v94, v95
	v_cvt_pk_bf16_f32 v82, v96, v97
	v_cvt_pk_bf16_f32 v83, v98, v99
	global_store_dwordx4 v65, v[80:83], s[6:7] offset:16 nt
	v_cvt_pk_bf16_f32 v40, v114, v115
	v_cvt_pk_bf16_f32 v41, v116, v117
	global_store_dwordx2 v66, v[40:41], s[100:101] nt
	v_cvt_pk_bf16_f32 v42, v118, v119
	v_cvt_pk_bf16_f32 v43, v120, v121
	global_store_dwordx2 v66, v[42:43], s[100:101] offset:2048 nt
	v_cvt_pk_bf16_f32 v44, v122, v123
	v_cvt_pk_bf16_f32 v45, v124, v125
	global_store_dwordx2 v67, v[44:45], s[100:101] nt
	v_cvt_pk_bf16_f32 v46, v126, v127
	v_cvt_pk_bf16_f32 v47, v128, v129
	global_store_dwordx2 v67, v[46:47], s[100:101] offset:2048 nt
	s_branch .Lgdn_p4_pad_end
	s_nop 0
	s_nop 0
	s_nop 0
	s_nop 0
	s_nop 0
	s_nop 0
	s_nop 0
	s_nop 0
	s_nop 0
	s_nop 0
	s_nop 0
	s_nop 0
	s_nop 0
	s_nop 0
	s_nop 0
	s_nop 0
	s_nop 0
	s_nop 0
	s_nop 0
	s_nop 0
	s_nop 0
	s_nop 0
	s_nop 0
	s_nop 0
	s_nop 0
	s_nop 0
	s_nop 0
	s_nop 0
	s_nop 0
	s_nop 0
	s_nop 0
	s_nop 0
	s_nop 0
	s_nop 0
	s_nop 0
	s_nop 0
	s_nop 0
	s_nop 0
	s_nop 0
	s_nop 0
	s_nop 0
	s_nop 0
	s_nop 0
	s_nop 0
	s_nop 0
	s_nop 0
	s_nop 0
	s_nop 0
	s_nop 0
	s_nop 0
	s_nop 0
	s_nop 0
	s_nop 0
	s_nop 0
	s_nop 0
	s_nop 0
	s_nop 0
	s_nop 0
	s_nop 0
	s_nop 0
	s_nop 0
	s_nop 0
	s_nop 0
	s_nop 0
	s_nop 0
	s_nop 0
	s_nop 0
	s_nop 0
	s_nop 0
	s_nop 0
	s_nop 0
	s_nop 0
	s_nop 0
	s_nop 0
	s_nop 0
	s_nop 0
	s_nop 0
	s_nop 0
	s_nop 0
	s_nop 0
	s_nop 0
	s_nop 0
	s_nop 0
	s_nop 0
	s_nop 0
	s_nop 0
	s_nop 0
	s_nop 0
	s_nop 0
	s_nop 0
	s_nop 0
	s_nop 0
	s_nop 0
	s_nop 0
	s_nop 0
	s_nop 0
	s_nop 0
	s_nop 0
	s_nop 0
	s_nop 0
	s_nop 0
	s_nop 0
	s_nop 0
	s_nop 0
	s_nop 0
	s_nop 0
	s_nop 0
	s_nop 0
	s_nop 0
	s_nop 0
	s_nop 0
	s_nop 0
	s_nop 0
	s_nop 0
	s_nop 0
	s_nop 0
	s_nop 0
	s_nop 0
	s_nop 0
	s_nop 0
	s_nop 0
	s_nop 0
	s_nop 0
	s_nop 0
	s_nop 0
	s_nop 0
	s_nop 0
	s_nop 0
	s_nop 0
	s_nop 0
	s_nop 0
	s_nop 0
	s_nop 0
	s_nop 0
	s_nop 0
	s_nop 0
	s_nop 0
	s_nop 0
	s_nop 0
	s_nop 0
	s_nop 0
	s_nop 0
	s_nop 0
	s_nop 0
	s_nop 0
	s_nop 0
	s_nop 0
	s_nop 0
	s_nop 0
	s_nop 0
	s_nop 0
	s_nop 0
	s_nop 0
	s_nop 0
	s_nop 0
	s_nop 0
	s_nop 0
	s_nop 0
	s_nop 0
	s_nop 0
	s_nop 0
	s_nop 0
	s_nop 0
	s_nop 0
	s_nop 0
	s_nop 0
	s_nop 0
	s_nop 0
	s_nop 0
	s_nop 0
	s_nop 0
	s_nop 0
	s_nop 0
	s_nop 0
	s_nop 0
	s_nop 0
	s_nop 0
	s_nop 0
	s_nop 0
	s_nop 0
	s_nop 0
	s_nop 0
	s_nop 0
	s_nop 0
	s_nop 0
	s_nop 0
	s_nop 0
	s_nop 0
	s_nop 0
	s_nop 0
	s_nop 0
	s_nop 0
	s_nop 0
	s_nop 0
	s_nop 0
	s_nop 0
	s_nop 0
	s_nop 0
	s_nop 0
	s_nop 0
	s_nop 0
	s_nop 0
	s_nop 0
	s_nop 0
	s_nop 0
	s_nop 0
	s_nop 0
	s_nop 0
	s_nop 0
	s_nop 0
	s_nop 0
	s_nop 0
	s_nop 0
	s_nop 0
	s_nop 0
	s_nop 0
	s_nop 0
	s_nop 0
	s_nop 0
	s_nop 0
	s_nop 0
	s_nop 0
	s_nop 0
	s_nop 0
	s_nop 0
	s_nop 0
	s_nop 0
	s_nop 0
	s_nop 0
	s_nop 0
	s_nop 0
	s_nop 0
	s_nop 0
	s_nop 0
	s_nop 0
	s_nop 0
	s_nop 0
	s_nop 0
	s_nop 0
	s_nop 0
	s_nop 0
	s_nop 0
	s_nop 0
	s_nop 0
	s_nop 0
	s_nop 0
	s_nop 0
	s_nop 0
	s_nop 0
	s_nop 0
	s_nop 0
	s_nop 0
	s_nop 0
	s_nop 0
	s_nop 0
	s_nop 0
	s_nop 0
	s_nop 0
	s_nop 0
	s_nop 0
	s_nop 0
	s_nop 0
	s_nop 0
	s_nop 0
	s_nop 0
	s_nop 0
	s_nop 0
	s_nop 0
	s_nop 0
	s_nop 0
	s_nop 0
	s_nop 0
	s_nop 0
	s_nop 0
	s_nop 0
	s_nop 0
	s_nop 0
	s_nop 0
	s_nop 0
	s_nop 0
	s_nop 0
	s_nop 0
	s_nop 0
	s_nop 0
	s_nop 0
	s_nop 0
	s_nop 0
	s_nop 0
	s_nop 0
	s_nop 0
	s_nop 0
	s_nop 0
	s_nop 0
	s_nop 0
	s_nop 0
	s_nop 0
	s_nop 0
	s_nop 0
	s_nop 0
	s_nop 0
	s_nop 0
	s_nop 0
	s_nop 0
	s_nop 0
	s_nop 0
	s_nop 0
	s_nop 0
	s_nop 0
	s_nop 0
	s_nop 0
	s_nop 0
	s_nop 0
	s_nop 0
	s_nop 0
	s_nop 0
	s_nop 0
	s_nop 0
	s_nop 0
	s_nop 0
	s_nop 0
	s_nop 0
	s_nop 0
	s_nop 0
	s_nop 0
	s_nop 0
	s_nop 0
	s_nop 0
	s_nop 0
	s_nop 0
	s_nop 0
	s_nop 0
	s_nop 0
	s_nop 0
	s_nop 0
	s_nop 0
	s_nop 0
	s_nop 0
	s_nop 0
	s_nop 0
	s_nop 0
	s_nop 0
	s_nop 0
	s_nop 0
	s_nop 0
	s_nop 0
	s_nop 0
	s_nop 0
	s_nop 0
	s_nop 0
	s_nop 0
	s_nop 0
	s_nop 0
	s_nop 0
	s_nop 0
	s_nop 0
	s_nop 0
	s_nop 0

; __device__ __forceinline__ bf16_t f2bf(float f) { return (bf16_t)(pk2(f, 0.f) & 0xffffu); }
; __device__ __forceinline__ float fexp(float x) { return __expf(x); }
; #define LBAR() do { asm volatile("s_waitcnt lgkmcnt(0)" ::: "memory"); __builtin_amdgcn_s_barrier(); asm volatile("" ::: "memory"); } while (0)
; __device__ __forceinline__ void ret_unit(const Ctx& X, LAS unsigned char* hl, int b, int c, int h, int tid_h, int w4, int lane) {
;     ...
; #pragma unroll
;     for (int ct = 0; ct < 4; ++ct) acc[ct] = mma16(QR, 16 * w4, KR, 16 * ct, (f32x4){0.f, 0.f, 0.f, 0.f}, r, q);
; #pragma unroll
;     for (int ct = 0; ct < 4; ++ct)
; #pragma unroll
;         for (int j = 0; j < 4; ++j) { const int ii = 16 * w4 + 4 * q + j, col = 16 * ct + r;
;             P[ii * LT + col] = f2bf(ii >= col ? acc[ct][j] * fexp(lg * (float)(ii - col)) : 0.f); }
;     LBAR();
.LpfR_done:
	v_or_b32_e32 v6, s39, v32
	v_mul_u32_u24_e32 v19, 0x90, v6
	v_add3_u32 v10, v37, v19, v20
	v_mad_u32_u24 v14, v32, s44, v29
	ds_read_b128 v[6:9], v10
	ds_read_b128 v[38:41], v10 offset:64
	ds_read_b128 v[10:13], v14
	ds_read_b128 v[14:17], v14 offset:64
	s_waitcnt lgkmcnt(1)
	v_mfma_f32_16x16x32_bf16 v[10:13], v[6:9], v[10:13], 0
	v_ashrrev_i32_e32 v18, 4, v130
	v_or_b32_e32 v31, 16, v32
	v_or_b32_e32 v28, 32, v32
	s_waitcnt lgkmcnt(0)
	v_mfma_f32_16x16x32_bf16 v[42:45], v[38:41], v[14:17], v[10:13]
	s_add_u32 s4, s79, s0
	s_addc_u32 s5, s80, s1
	s_add_u32 s0, s74, s0
	v_mov_b32_e32 v10, 0x900
	v_mad_u32_u24 v21, v32, s44, v10
	v_add_u32_e32 v14, v29, v21
	ds_read_b128 v[10:13], v14
	ds_read_b128 v[14:17], v14 offset:64
	s_waitcnt lgkmcnt(1)
	v_mfma_f32_16x16x32_bf16 v[10:13], v[6:9], v[10:13], 0
	s_addc_u32 s1, s75, s1
	s_waitcnt lgkmcnt(0)
	v_mfma_f32_16x16x32_bf16 v[14:17], v[38:41], v[14:17], v[10:13]
	s_nop 4
	v_mov_b32_e32 v10, 0x1200
	v_mad_u32_u24 v22, v32, s44, v10
	v_add_u32_e32 v23, v29, v22
	ds_read_b128 v[10:13], v23
	ds_read_b128 v[24:27], v23 offset:64
	s_waitcnt lgkmcnt(1)
	v_mfma_f32_16x16x32_bf16 v[10:13], v[6:9], v[10:13], 0
	v_mov_b32_e32 v23, 0x1b00
	v_mad_u32_u24 v23, v32, s44, v23
	s_waitcnt lgkmcnt(0)
	v_mfma_f32_16x16x32_bf16 v[10:13], v[38:41], v[24:27], v[10:13]
	v_lshl_add_u32 v27, v18, 2, s39
	v_sub_u32_e32 v26, v27, v32
	v_cvt_f32_i32_e32 v26, v26
	v_add_u32_e32 v25, v29, v23
	ds_read_b128 v[46:49], v25
	v_cmp_ge_i32_e32 vcc, v27, v32
	v_mul_f32_e32 v26, v36, v26
	v_mul_f32_e32 v26, 0x3fb8aa3b, v26
	v_exp_f32_e32 v26, v26
	s_waitcnt lgkmcnt(0)
	v_mfma_f32_16x16x32_bf16 v[6:9], v[6:9], v[46:49], 0
	ds_read_b128 v[46:49], v25 offset:64
	v_lshlrev_b32_e32 v25, 1, v32
	v_mul_f32_e32 v26, v26, v42
	v_cndmask_b32_e32 v26, 0, v26, vcc
	v_mul_lo_u32 v29, v27, s44
	v_cvt_pk_bf16_f32 v26, v26, v157
	v_add3_u32 v25, v35, v25, v29
	v_or_b32_e32 v30, 1, v27
	ds_write_b16 v25, v26
	v_sub_u32_e32 v26, v30, v32
	v_cvt_f32_i32_e32 v26, v26
	v_cmp_ge_i32_e32 vcc, v30, v32
	v_or_b32_e32 v29, 2, v27
	v_or_b32_e32 v24, 48, v32
	v_mul_f32_e32 v26, v36, v26
	v_mul_f32_e32 v26, 0x3fb8aa3b, v26
	v_exp_f32_e32 v26, v26
	s_waitcnt lgkmcnt(1)
	v_mfma_f32_16x16x32_bf16 v[6:9], v[38:41], v[46:49], v[6:9]
	v_add_u32_e32 v38, v34, v20
	v_mad_u32_u24 v39, v32, s44, v38
	v_mul_f32_e32 v26, v26, v43
	v_cndmask_b32_e32 v26, 0, v26, vcc
	v_cvt_pk_bf16_f32 v26, v26, v157
	ds_write_b16 v25, v26 offset:144
	v_sub_u32_e32 v26, v29, v32
	v_cvt_f32_i32_e32 v26, v26
	v_cmp_ge_i32_e32 vcc, v29, v32
	v_add_u32_e32 v40, v38, v21
	v_add_u32_e32 v41, v38, v22
	v_mul_f32_e32 v26, v36, v26
	v_mul_f32_e32 v26, 0x3fb8aa3b, v26
	v_exp_f32_e32 v26, v26
	v_add_u32_e32 v38, v38, v23
	v_mul_f32_e32 v26, v26, v44
	v_cndmask_b32_e32 v26, 0, v26, vcc
	v_cvt_pk_bf16_f32 v26, v26, v157
	ds_write_b16 v25, v26 offset:288
	v_or_b32_e32 v26, 3, v27
	v_sub_u32_e32 v37, v26, v32
	v_cvt_f32_i32_e32 v37, v37
	v_cmp_ge_i32_e32 vcc, v26, v32
	v_mul_f32_e32 v37, v36, v37
	v_mul_f32_e32 v37, 0x3fb8aa3b, v37
	v_exp_f32_e32 v37, v37
	s_nop 0
	v_mul_f32_e32 v37, v37, v45
	v_cndmask_b32_e32 v37, 0, v37, vcc
	v_cvt_pk_bf16_f32 v37, v37, v157
	ds_write_b16 v25, v37 offset:432
	v_sub_u32_e32 v37, v27, v31
	v_cvt_f32_i32_e32 v37, v37
	v_cmp_ge_i32_e32 vcc, v27, v31
	v_mul_f32_e32 v37, v36, v37
	v_mul_f32_e32 v37, 0x3fb8aa3b, v37
	v_exp_f32_e32 v37, v37
	s_nop 0
	v_mul_f32_e32 v14, v37, v14
	v_cndmask_b32_e32 v14, 0, v14, vcc
	v_cvt_pk_bf16_f32 v14, v14, v157
	ds_write_b16 v25, v14 offset:32
	v_sub_u32_e32 v14, v30, v31
	v_cvt_f32_i32_e32 v14, v14
	v_cmp_ge_i32_e32 vcc, v30, v31
	v_mul_f32_e32 v14, v36, v14
	v_mul_f32_e32 v14, 0x3fb8aa3b, v14
	v_exp_f32_e32 v14, v14
	s_nop 0
	v_mul_f32_e32 v14, v14, v15
	v_cndmask_b32_e32 v14, 0, v14, vcc
	v_cvt_pk_bf16_f32 v14, v14, v157
	ds_write_b16 v25, v14 offset:176
	v_sub_u32_e32 v14, v29, v31
	v_cvt_f32_i32_e32 v14, v14
	v_cmp_ge_i32_e32 vcc, v29, v31
	v_mul_f32_e32 v14, v36, v14
	v_mul_f32_e32 v14, 0x3fb8aa3b, v14
	v_exp_f32_e32 v14, v14
	s_nop 0
	v_mul_f32_e32 v14, v14, v16
	v_cndmask_b32_e32 v14, 0, v14, vcc
	v_cvt_pk_bf16_f32 v14, v14, v157
	ds_write_b16 v25, v14 offset:320
	v_sub_u32_e32 v14, v26, v31
	v_cvt_f32_i32_e32 v14, v14
	v_cmp_ge_i32_e32 vcc, v26, v31
	v_mul_f32_e32 v14, v36, v14
	v_mul_f32_e32 v14, 0x3fb8aa3b, v14
	v_exp_f32_e32 v14, v14
	s_nop 0
	v_mul_f32_e32 v14, v14, v17
	v_cndmask_b32_e32 v14, 0, v14, vcc
	v_cvt_pk_bf16_f32 v14, v14, v157
	ds_write_b16 v25, v14 offset:464
	v_sub_u32_e32 v14, v27, v28
	v_cvt_f32_i32_e32 v14, v14
	v_cmp_ge_i32_e32 vcc, v27, v28
	v_mul_f32_e32 v14, v36, v14
	v_mul_f32_e32 v14, 0x3fb8aa3b, v14
	v_exp_f32_e32 v14, v14
	s_nop 0
	v_mul_f32_e32 v10, v14, v10
	v_cndmask_b32_e32 v10, 0, v10, vcc
	v_cvt_pk_bf16_f32 v10, v10, v157
	ds_write_b16 v25, v10 offset:64
	v_sub_u32_e32 v10, v30, v28
	v_cvt_f32_i32_e32 v10, v10
	v_cmp_ge_i32_e32 vcc, v30, v28
	v_mul_f32_e32 v10, v36, v10
	v_mul_f32_e32 v10, 0x3fb8aa3b, v10
	v_exp_f32_e32 v10, v10
	s_nop 0
	v_mul_f32_e32 v10, v10, v11
	v_cndmask_b32_e32 v10, 0, v10, vcc
	v_cvt_pk_bf16_f32 v10, v10, v157
	ds_write_b16 v25, v10 offset:208
	v_sub_u32_e32 v10, v29, v28
	v_cvt_f32_i32_e32 v10, v10
	v_cmp_ge_i32_e32 vcc, v29, v28
	v_mul_f32_e32 v10, v36, v10
	v_mul_f32_e32 v10, 0x3fb8aa3b, v10
	v_exp_f32_e32 v10, v10
	s_nop 0
	v_mul_f32_e32 v10, v10, v12
	v_cndmask_b32_e32 v10, 0, v10, vcc
	v_cvt_pk_bf16_f32 v10, v10, v157
	ds_write_b16 v25, v10 offset:352
	v_sub_u32_e32 v10, v26, v28
	v_cvt_f32_i32_e32 v10, v10
	v_cmp_ge_i32_e32 vcc, v26, v28
	v_mul_f32_e32 v10, v36, v10
	v_mul_f32_e32 v10, 0x3fb8aa3b, v10
	v_exp_f32_e32 v10, v10
	s_nop 0
	v_mul_f32_e32 v10, v10, v13
	v_cndmask_b32_e32 v10, 0, v10, vcc
	v_cvt_pk_bf16_f32 v10, v10, v157
	ds_write_b16 v25, v10 offset:496
	v_sub_u32_e32 v10, v27, v24
	v_cvt_f32_i32_e32 v10, v10
	v_cmp_ge_i32_e32 vcc, v27, v24
	v_mul_f32_e32 v10, v36, v10
	v_mul_f32_e32 v10, 0x3fb8aa3b, v10
	v_exp_f32_e32 v10, v10
	s_nop 0
	v_mul_f32_e32 v6, v10, v6
	v_cndmask_b32_e32 v6, 0, v6, vcc
	v_cvt_pk_bf16_f32 v6, v6, v157
	ds_write_b16 v25, v6 offset:96
	v_sub_u32_e32 v6, v30, v24
	v_cvt_f32_i32_e32 v6, v6
	v_cmp_ge_i32_e32 vcc, v30, v24
	v_add3_u32 v10, v35, v19, v20
	v_mul_f32_e32 v6, v36, v6
	v_mul_f32_e32 v6, 0x3fb8aa3b, v6
	v_exp_f32_e32 v6, v6
	s_nop 0
	v_mul_f32_e32 v6, v6, v7
	v_cndmask_b32_e32 v6, 0, v6, vcc
	v_cvt_pk_bf16_f32 v6, v6, v157
	ds_write_b16 v25, v6 offset:240
	v_sub_u32_e32 v6, v29, v24
	v_cvt_f32_i32_e32 v6, v6
	v_cmp_ge_i32_e32 vcc, v29, v24
	v_mul_f32_e32 v6, v36, v6
	v_mul_f32_e32 v6, 0x3fb8aa3b, v6
	v_exp_f32_e32 v6, v6
	s_nop 0
	v_mul_f32_e32 v6, v6, v8
	v_cndmask_b32_e32 v6, 0, v6, vcc
	v_cvt_pk_bf16_f32 v6, v6, v157
	ds_write_b16 v25, v6 offset:384
	v_sub_u32_e32 v6, v26, v24
	v_cvt_f32_i32_e32 v6, v6
	v_cmp_ge_i32_e32 vcc, v26, v24
	v_mul_f32_e32 v6, v36, v6
	v_mul_f32_e32 v6, 0x3fb8aa3b, v6
	v_exp_f32_e32 v6, v6
	s_nop 0
	v_mul_f32_e32 v6, v6, v9
	v_cndmask_b32_e32 v6, 0, v6, vcc
	v_cvt_pk_bf16_f32 v6, v6, v157
	ds_write_b16 v25, v6 offset:528
	s_waitcnt lgkmcnt(0)
	s_barrier
; #define LBAR() do { asm volatile("s_waitcnt lgkmcnt(0)" ::: "memory"); __builtin_amdgcn_s_barrier(); asm volatile("" ::: "memory"); } while (0)
; __device__ __forceinline__ void ret_unit(const Ctx& X, LAS unsigned char* hl, int b, int c, int h, int tid_h, int w4, int lane) {
;     ...
; #pragma unroll
;     for (int ct = 0; ct < 4; ++ct) acc[ct] = mma16(P, 16 * w4, VT, 16 * ct, (f32x4){0.f, 0.f, 0.f, 0.f}, r, q);
;     store_oloc(WSP(bf16_t, WS_OLOC), uid, w4, lane, acc);
; #pragma unroll
;     for (int ct = 0; ct < 4; ++ct) acc[ct] = mma16(KDT, 16 * w4, VT, 16 * ct, (f32x4){0.f, 0.f, 0.f, 0.f}, r, q);
;     store_bc(WSP(bf16_t, WS_BCS), uid, w4, r, q, acc);
;     LBAR();
	v_add3_u32 v42, v33, v19, v20
	ds_read_b128 v[46:49], v10
	ds_read_b128 v[50:53], v10 offset:64
	ds_read_b128 v[54:57], v39
	ds_read_b128 v[58:61], v39 offset:64
	ds_read_b128 v[62:65], v40
	ds_read_b128 v[66:69], v40 offset:64
	ds_read_b128 v[72:75], v41
	ds_read_b128 v[76:79], v41 offset:64
	ds_read_b128 v[80:83], v38
	ds_read_b128 v[102:105], v38 offset:64
	ds_read_b128 v[134:137], v42
	ds_read_b128 v[138:141], v42 offset:64
	v_lshlrev_b32_e32 v6, 4, v130
	v_ashrrev_i32_e32 v7, 31, v6
	v_lshl_add_u64 v[22:23], v[6:7], 1, s[4:5]
	v_lshl_or_b32 v12, v32, 2, s81
	v_lshl_add_u32 v12, v18, 6, v12
	v_ashrrev_i32_e32 v13, 31, v12
	v_lshl_add_u64 v[14:15], v[12:13], 1, s[0:1]
	v_add_u32_e32 v16, 0x800, v12
	v_ashrrev_i32_e32 v17, 31, v16
	v_lshl_add_u64 v[16:17], v[16:17], 1, s[0:1]
	v_add_u32_e32 v8, 0xc00, v12
	v_ashrrev_i32_e32 v9, 31, v8
	v_lshl_add_u64 v[8:9], v[8:9], 1, s[0:1]
	s_waitcnt lgkmcnt(2)
	v_mfma_f32_16x16x32_bf16 v[186:189], v[46:49], v[54:57], 0
	v_mfma_f32_16x16x32_bf16 v[190:193], v[46:49], v[62:65], 0
	v_mfma_f32_16x16x32_bf16 v[194:197], v[46:49], v[72:75], 0
	v_mfma_f32_16x16x32_bf16 v[198:201], v[46:49], v[80:83], 0
	v_mfma_f32_16x16x32_bf16 v[186:189], v[50:53], v[58:61], v[186:189]
	v_mfma_f32_16x16x32_bf16 v[190:193], v[50:53], v[66:69], v[190:193]
	v_mfma_f32_16x16x32_bf16 v[194:197], v[50:53], v[76:79], v[194:197]
	v_mfma_f32_16x16x32_bf16 v[198:201], v[50:53], v[102:105], v[198:201]
	s_waitcnt lgkmcnt(0)
	v_mfma_f32_16x16x32_bf16 v[202:205], v[134:137], v[54:57], 0
	v_mfma_f32_16x16x32_bf16 v[206:209], v[134:137], v[62:65], 0
	v_mfma_f32_16x16x32_bf16 v[210:213], v[134:137], v[72:75], 0
	v_mfma_f32_16x16x32_bf16 v[214:217], v[134:137], v[80:83], 0
	v_mfma_f32_16x16x32_bf16 v[202:205], v[138:141], v[58:61], v[202:205]
	v_mfma_f32_16x16x32_bf16 v[206:209], v[138:141], v[66:69], v[206:209]
	v_mfma_f32_16x16x32_bf16 v[210:213], v[138:141], v[76:79], v[210:213]
	v_mfma_f32_16x16x32_bf16 v[214:217], v[138:141], v[102:105], v[214:217]
	v_cvt_pk_bf16_f32 v218, v186, v187
	v_cvt_pk_bf16_f32 v219, v188, v189
	v_cvt_pk_bf16_f32 v220, v190, v191
	v_cvt_pk_bf16_f32 v221, v192, v193
	v_cvt_pk_bf16_f32 v236, v194, v195
	v_cvt_pk_bf16_f32 v237, v196, v197
	v_cvt_pk_bf16_f32 v238, v198, v199
	v_cvt_pk_bf16_f32 v239, v200, v201
	global_store_dwordx4 v[22:23], v[218:221], off nt
	global_store_dwordx4 v[22:23], v[236:239], off offset:16 nt
	v_cvt_pk_bf16_f32 v246, v202, v203
	v_cvt_pk_bf16_f32 v247, v204, v205
	v_cvt_pk_bf16_f32 v248, v206, v207
	v_cvt_pk_bf16_f32 v249, v208, v209
	v_cvt_pk_bf16_f32 v250, v210, v211
	v_cvt_pk_bf16_f32 v251, v212, v213
	v_cvt_pk_bf16_f32 v226, v214, v215
	v_cvt_pk_bf16_f32 v227, v216, v217
	global_store_dwordx2 v[14:15], v[246:247], off nt
	global_store_dwordx2 v[14:15], v[248:249], off offset:2048 nt
	global_store_dwordx2 v[16:17], v[250:251], off nt
	global_store_dwordx2 v[8:9], v[226:227], off nt
	s_waitcnt lgkmcnt(0)
	s_barrier
	s_branch .LBB0_233
